# swapped-operand FFN-up epilogue with non-temporal (nt) hb stores: partial-line writes no longer wait for an L2 line fill
# speedup vs baseline: 1.0092x; 1.0092x over previous
.Lffn_nz:
	s_waitcnt vmcnt(0)
	ds_bpermute_b32 v200, v252, v158
	ds_bpermute_b32 v201, v252, v159
	ds_bpermute_b32 v202, v252, v154
	ds_bpermute_b32 v203, v252, v155
	s_waitcnt lgkmcnt(0)
	ds_bpermute_b32 v204, v252, v62
	ds_bpermute_b32 v205, v252, v63
	ds_bpermute_b32 v206, v252, v58
	ds_bpermute_b32 v207, v252, v59
	v_pk_fma_f32 v[230:231], v[156:157], v[112:113], v[116:117] op_sel_hi:[1,0,0]
	v_pk_fma_f32 v[232:233], v[158:159], v[112:113], v[116:117] op_sel_hi:[1,0,0]
	v_fmac_f32_e32 v230, v201, v113
	v_fmac_f32_e32 v231, v156, v113
	v_fmac_f32_e32 v232, v157, v113
	v_fmac_f32_e32 v233, v158, v113
	v_pk_fma_f32 v[230:231], v[200:201], v[114:115], v[230:231] op_sel_hi:[1,0,1]
	v_pk_fma_f32 v[232:233], v[156:157], v[114:115], v[232:233] op_sel_hi:[1,0,1]
	v_pk_fma_f32 v[234:235], v[152:153], v[118:119], v[122:123] op_sel_hi:[1,0,0]
	v_pk_fma_f32 v[236:237], v[154:155], v[118:119], v[122:123] op_sel_hi:[1,0,0]
	v_fmac_f32_e32 v234, v203, v119
	v_fmac_f32_e32 v235, v152, v119
	v_fmac_f32_e32 v236, v153, v119
	v_fmac_f32_e32 v237, v154, v119
	v_pk_fma_f32 v[234:235], v[202:203], v[120:121], v[234:235] op_sel_hi:[1,0,1]
	v_pk_fma_f32 v[236:237], v[152:153], v[120:121], v[236:237] op_sel_hi:[1,0,1]
	v_pk_mul_f32 v[238:239], v[230:231], v[230:231]
	v_pk_mul_f32 v[240:241], v[232:233], v[232:233]
	v_pk_fma_f32 v[238:239], v[238:239], v[248:249], v[246:247]
	v_pk_fma_f32 v[240:241], v[240:241], v[248:249], v[246:247]
	v_pk_mul_f32 v[238:239], v[230:231], v[238:239]
	v_pk_mul_f32 v[240:241], v[232:233], v[240:241]
	v_exp_f32_e32 v238, v238
	v_exp_f32_e32 v239, v239
	v_exp_f32_e32 v240, v240
	v_exp_f32_e32 v241, v241
	v_pk_add_f32 v[238:239], v[238:239], 1.0 op_sel_hi:[1,0]
	v_pk_add_f32 v[240:241], v[240:241], 1.0 op_sel_hi:[1,0]
	v_rcp_f32_e32 v238, v238
	v_rcp_f32_e32 v239, v239
	v_rcp_f32_e32 v240, v240
	v_rcp_f32_e32 v241, v241
	v_pk_mul_f32 v[230:231], v[230:231], v[234:235]
	v_pk_mul_f32 v[232:233], v[232:233], v[236:237]
	v_pk_mul_f32 v[238:239], v[230:231], v[238:239]
	v_pk_mul_f32 v[240:241], v[232:233], v[240:241]
	v_cvt_pk_bf16_f32 v212, v238, v239
	v_cvt_pk_bf16_f32 v213, v240, v241
	s_mov_b64 vcc, s[30:31]
	s_nop 0
	v_mov_b32_dpp v214, v212 quad_perm:[1,0,3,2] row_mask:0xf bank_mask:0xf
	v_mov_b32_dpp v215, v213 quad_perm:[1,0,3,2] row_mask:0xf bank_mask:0xf
	v_perm_b32 v216, v214, v212, v253
	v_perm_b32 v217, v215, v213, v253
	s_nop 1
	v_mov_b32_dpp v218, v216 quad_perm:[2,3,0,1] row_mask:0xf bank_mask:0xf
	v_mov_b32_dpp v219, v217 quad_perm:[2,3,0,1] row_mask:0xf bank_mask:0xf
	v_cndmask_b32_e32 v176, v216, v219, vcc
	v_cndmask_b32_e32 v177, v218, v217, vcc
	s_waitcnt lgkmcnt(0)
	s_mov_b64 vcc, s[28:29]
	v_cndmask_b32_e32 v208, v150, v158, vcc
	v_cndmask_b32_e32 v209, v151, v159, vcc
	v_cndmask_b32_e32 v210, v146, v154, vcc
	v_cndmask_b32_e32 v211, v147, v155, vcc
	ds_bpermute_b32 v200, v252, v208
	ds_bpermute_b32 v201, v252, v209
	ds_bpermute_b32 v202, v252, v210
	ds_bpermute_b32 v203, v252, v211
	v_pk_fma_f32 v[230:231], v[60:61], v[124:125], v[128:129] op_sel_hi:[1,0,0]
	v_pk_fma_f32 v[232:233], v[62:63], v[124:125], v[128:129] op_sel_hi:[1,0,0]
	v_fmac_f32_e32 v230, v205, v125
	v_fmac_f32_e32 v231, v60, v125
	v_fmac_f32_e32 v232, v61, v125
	v_fmac_f32_e32 v233, v62, v125
	v_pk_fma_f32 v[230:231], v[204:205], v[126:127], v[230:231] op_sel_hi:[1,0,1]
	v_pk_fma_f32 v[232:233], v[60:61], v[126:127], v[232:233] op_sel_hi:[1,0,1]
	v_pk_fma_f32 v[234:235], v[56:57], v[130:131], v[134:135] op_sel_hi:[1,0,0]
	v_pk_fma_f32 v[236:237], v[58:59], v[130:131], v[134:135] op_sel_hi:[1,0,0]
	v_fmac_f32_e32 v234, v207, v131
	v_fmac_f32_e32 v235, v56, v131
	v_fmac_f32_e32 v236, v57, v131
	v_fmac_f32_e32 v237, v58, v131
	v_pk_fma_f32 v[234:235], v[206:207], v[132:133], v[234:235] op_sel_hi:[1,0,1]
	v_pk_fma_f32 v[236:237], v[56:57], v[132:133], v[236:237] op_sel_hi:[1,0,1]
	v_pk_mul_f32 v[238:239], v[230:231], v[230:231]
	v_pk_mul_f32 v[240:241], v[232:233], v[232:233]
	v_pk_fma_f32 v[238:239], v[238:239], v[248:249], v[246:247]
	v_pk_fma_f32 v[240:241], v[240:241], v[248:249], v[246:247]
	v_pk_mul_f32 v[238:239], v[230:231], v[238:239]
	v_pk_mul_f32 v[240:241], v[232:233], v[240:241]
	v_exp_f32_e32 v238, v238
	v_exp_f32_e32 v239, v239
	v_exp_f32_e32 v240, v240
	v_exp_f32_e32 v241, v241
	v_pk_add_f32 v[238:239], v[238:239], 1.0 op_sel_hi:[1,0]
	v_pk_add_f32 v[240:241], v[240:241], 1.0 op_sel_hi:[1,0]
	v_rcp_f32_e32 v238, v238
	v_rcp_f32_e32 v239, v239
	v_rcp_f32_e32 v240, v240
	v_rcp_f32_e32 v241, v241
	v_pk_mul_f32 v[230:231], v[230:231], v[234:235]
	v_pk_mul_f32 v[232:233], v[232:233], v[236:237]
	v_pk_mul_f32 v[238:239], v[230:231], v[238:239]
	v_pk_mul_f32 v[240:241], v[232:233], v[240:241]
	v_cvt_pk_bf16_f32 v212, v238, v239
	v_cvt_pk_bf16_f32 v213, v240, v241
	s_mov_b64 vcc, s[30:31]
	s_nop 0
	v_mov_b32_dpp v214, v212 quad_perm:[1,0,3,2] row_mask:0xf bank_mask:0xf
	v_mov_b32_dpp v215, v213 quad_perm:[1,0,3,2] row_mask:0xf bank_mask:0xf
	v_perm_b32 v216, v214, v212, v253
	v_perm_b32 v217, v215, v213, v253
	s_nop 1
	v_mov_b32_dpp v218, v216 quad_perm:[2,3,0,1] row_mask:0xf bank_mask:0xf
	v_mov_b32_dpp v219, v217 quad_perm:[2,3,0,1] row_mask:0xf bank_mask:0xf
	v_cndmask_b32_e32 v178, v216, v219, vcc
	v_cndmask_b32_e32 v179, v218, v217, vcc
	s_movk_i32 s15, 0x1002
	v_cmp_gt_i32_e64 s[24:25], s15, v251
	s_sub_u32 s84, s58, 0x2c00
	s_subb_u32 s85, s59, 0
	s_and_b64 s[24:25], s[24:25], s[36:37]
	s_mov_b64 exec, s[24:25]
	global_store_dwordx4 v250, v[176:179], s[84:85] nt
	s_mov_b64 exec, -1
	s_nop 0
	s_waitcnt lgkmcnt(0)
	s_mov_b64 vcc, s[28:29]
	v_cndmask_b32_e32 v208, v54, v62, vcc
	v_cndmask_b32_e32 v209, v55, v63, vcc
	v_cndmask_b32_e32 v210, v50, v58, vcc
	v_cndmask_b32_e32 v211, v51, v59, vcc
	ds_bpermute_b32 v204, v252, v208
	ds_bpermute_b32 v205, v252, v209
	ds_bpermute_b32 v206, v252, v210
	ds_bpermute_b32 v207, v252, v211
	v_pk_fma_f32 v[230:231], v[148:149], v[112:113], v[116:117] op_sel_hi:[1,0,0]
	v_pk_fma_f32 v[232:233], v[150:151], v[112:113], v[116:117] op_sel_hi:[1,0,0]
	v_fmac_f32_e32 v230, v201, v113
	v_fmac_f32_e32 v231, v148, v113
	v_fmac_f32_e32 v232, v149, v113
	v_fmac_f32_e32 v233, v150, v113
	v_pk_fma_f32 v[230:231], v[200:201], v[114:115], v[230:231] op_sel_hi:[1,0,1]
	v_pk_fma_f32 v[232:233], v[148:149], v[114:115], v[232:233] op_sel_hi:[1,0,1]
	v_pk_fma_f32 v[234:235], v[144:145], v[118:119], v[122:123] op_sel_hi:[1,0,0]
	v_pk_fma_f32 v[236:237], v[146:147], v[118:119], v[122:123] op_sel_hi:[1,0,0]
	v_fmac_f32_e32 v234, v203, v119
	v_fmac_f32_e32 v235, v144, v119
	v_fmac_f32_e32 v236, v145, v119
	v_fmac_f32_e32 v237, v146, v119
	v_pk_fma_f32 v[234:235], v[202:203], v[120:121], v[234:235] op_sel_hi:[1,0,1]
	v_pk_fma_f32 v[236:237], v[144:145], v[120:121], v[236:237] op_sel_hi:[1,0,1]
	v_pk_mul_f32 v[238:239], v[230:231], v[230:231]
	v_pk_mul_f32 v[240:241], v[232:233], v[232:233]
	v_pk_fma_f32 v[238:239], v[238:239], v[248:249], v[246:247]
	v_pk_fma_f32 v[240:241], v[240:241], v[248:249], v[246:247]
	v_pk_mul_f32 v[238:239], v[230:231], v[238:239]
	v_pk_mul_f32 v[240:241], v[232:233], v[240:241]
	v_exp_f32_e32 v238, v238
	v_exp_f32_e32 v239, v239
	v_exp_f32_e32 v240, v240
	v_exp_f32_e32 v241, v241
	v_pk_add_f32 v[238:239], v[238:239], 1.0 op_sel_hi:[1,0]
	v_pk_add_f32 v[240:241], v[240:241], 1.0 op_sel_hi:[1,0]
	v_rcp_f32_e32 v238, v238
	v_rcp_f32_e32 v239, v239
	v_rcp_f32_e32 v240, v240
	v_rcp_f32_e32 v241, v241
	v_pk_mul_f32 v[230:231], v[230:231], v[234:235]
	v_pk_mul_f32 v[232:233], v[232:233], v[236:237]
	v_pk_mul_f32 v[238:239], v[230:231], v[238:239]
	v_pk_mul_f32 v[240:241], v[232:233], v[240:241]
	v_cvt_pk_bf16_f32 v212, v238, v239
	v_cvt_pk_bf16_f32 v213, v240, v241
	s_mov_b64 vcc, s[30:31]
	s_nop 0
	v_mov_b32_dpp v214, v212 quad_perm:[1,0,3,2] row_mask:0xf bank_mask:0xf
	v_mov_b32_dpp v215, v213 quad_perm:[1,0,3,2] row_mask:0xf bank_mask:0xf
	v_perm_b32 v216, v214, v212, v253
	v_perm_b32 v217, v215, v213, v253
	s_nop 1
	v_mov_b32_dpp v218, v216 quad_perm:[2,3,0,1] row_mask:0xf bank_mask:0xf
	v_mov_b32_dpp v219, v217 quad_perm:[2,3,0,1] row_mask:0xf bank_mask:0xf
	v_cndmask_b32_e32 v180, v216, v219, vcc
	v_cndmask_b32_e32 v181, v218, v217, vcc
	s_waitcnt lgkmcnt(0)
	s_mov_b64 vcc, s[28:29]
	v_cndmask_b32_e32 v208, v142, v150, vcc
	v_cndmask_b32_e32 v209, v143, v151, vcc
	v_cndmask_b32_e32 v210, v138, v146, vcc
	v_cndmask_b32_e32 v211, v139, v147, vcc
	ds_bpermute_b32 v200, v252, v208
	ds_bpermute_b32 v201, v252, v209
	ds_bpermute_b32 v202, v252, v210
	ds_bpermute_b32 v203, v252, v211
	v_pk_fma_f32 v[230:231], v[52:53], v[124:125], v[128:129] op_sel_hi:[1,0,0]
	v_pk_fma_f32 v[232:233], v[54:55], v[124:125], v[128:129] op_sel_hi:[1,0,0]
	v_fmac_f32_e32 v230, v205, v125
	v_fmac_f32_e32 v231, v52, v125
	v_fmac_f32_e32 v232, v53, v125
	v_fmac_f32_e32 v233, v54, v125
	v_pk_fma_f32 v[230:231], v[204:205], v[126:127], v[230:231] op_sel_hi:[1,0,1]
	v_pk_fma_f32 v[232:233], v[52:53], v[126:127], v[232:233] op_sel_hi:[1,0,1]
	v_pk_fma_f32 v[234:235], v[48:49], v[130:131], v[134:135] op_sel_hi:[1,0,0]
	v_pk_fma_f32 v[236:237], v[50:51], v[130:131], v[134:135] op_sel_hi:[1,0,0]
	v_fmac_f32_e32 v234, v207, v131
	v_fmac_f32_e32 v235, v48, v131
	v_fmac_f32_e32 v236, v49, v131
	v_fmac_f32_e32 v237, v50, v131
	v_pk_fma_f32 v[234:235], v[206:207], v[132:133], v[234:235] op_sel_hi:[1,0,1]
	v_pk_fma_f32 v[236:237], v[48:49], v[132:133], v[236:237] op_sel_hi:[1,0,1]
	v_pk_mul_f32 v[238:239], v[230:231], v[230:231]
	v_pk_mul_f32 v[240:241], v[232:233], v[232:233]
	v_pk_fma_f32 v[238:239], v[238:239], v[248:249], v[246:247]
	v_pk_fma_f32 v[240:241], v[240:241], v[248:249], v[246:247]
	v_pk_mul_f32 v[238:239], v[230:231], v[238:239]
	v_pk_mul_f32 v[240:241], v[232:233], v[240:241]
	v_exp_f32_e32 v238, v238
	v_exp_f32_e32 v239, v239
	v_exp_f32_e32 v240, v240
	v_exp_f32_e32 v241, v241
	v_pk_add_f32 v[238:239], v[238:239], 1.0 op_sel_hi:[1,0]
	v_pk_add_f32 v[240:241], v[240:241], 1.0 op_sel_hi:[1,0]
	v_rcp_f32_e32 v238, v238
	v_rcp_f32_e32 v239, v239
	v_rcp_f32_e32 v240, v240
	v_rcp_f32_e32 v241, v241
	v_pk_mul_f32 v[230:231], v[230:231], v[234:235]
	v_pk_mul_f32 v[232:233], v[232:233], v[236:237]
	v_pk_mul_f32 v[238:239], v[230:231], v[238:239]
	v_pk_mul_f32 v[240:241], v[232:233], v[240:241]
	v_cvt_pk_bf16_f32 v212, v238, v239
	v_cvt_pk_bf16_f32 v213, v240, v241
	s_mov_b64 vcc, s[30:31]
	s_nop 0
	v_mov_b32_dpp v214, v212 quad_perm:[1,0,3,2] row_mask:0xf bank_mask:0xf
	v_mov_b32_dpp v215, v213 quad_perm:[1,0,3,2] row_mask:0xf bank_mask:0xf
	v_perm_b32 v216, v214, v212, v253
	v_perm_b32 v217, v215, v213, v253
	s_nop 1
	v_mov_b32_dpp v218, v216 quad_perm:[2,3,0,1] row_mask:0xf bank_mask:0xf
	v_mov_b32_dpp v219, v217 quad_perm:[2,3,0,1] row_mask:0xf bank_mask:0xf
	v_cndmask_b32_e32 v182, v216, v219, vcc
	v_cndmask_b32_e32 v183, v218, v217, vcc
	s_movk_i32 s15, 0xff2
	v_cmp_gt_i32_e64 s[24:25], s15, v251
	s_add_u32 s84, s58, 0x13400
	s_addc_u32 s85, s59, 0
	s_mov_b64 exec, s[24:25]
	global_store_dwordx4 v250, v[180:183], s[84:85] nt
	s_mov_b64 exec, -1
	s_nop 0
	s_waitcnt lgkmcnt(0)
	s_mov_b64 vcc, s[28:29]
	v_cndmask_b32_e32 v208, v46, v54, vcc
	v_cndmask_b32_e32 v209, v47, v55, vcc
	v_cndmask_b32_e32 v210, v42, v50, vcc
	v_cndmask_b32_e32 v211, v43, v51, vcc
	ds_bpermute_b32 v204, v252, v208
	ds_bpermute_b32 v205, v252, v209
	ds_bpermute_b32 v206, v252, v210
	ds_bpermute_b32 v207, v252, v211
	v_pk_fma_f32 v[230:231], v[140:141], v[112:113], v[116:117] op_sel_hi:[1,0,0]
	v_pk_fma_f32 v[232:233], v[142:143], v[112:113], v[116:117] op_sel_hi:[1,0,0]
	v_fmac_f32_e32 v230, v201, v113
	v_fmac_f32_e32 v231, v140, v113
	v_fmac_f32_e32 v232, v141, v113
	v_fmac_f32_e32 v233, v142, v113
	v_pk_fma_f32 v[230:231], v[200:201], v[114:115], v[230:231] op_sel_hi:[1,0,1]
	v_pk_fma_f32 v[232:233], v[140:141], v[114:115], v[232:233] op_sel_hi:[1,0,1]
	v_pk_fma_f32 v[234:235], v[136:137], v[118:119], v[122:123] op_sel_hi:[1,0,0]
	v_pk_fma_f32 v[236:237], v[138:139], v[118:119], v[122:123] op_sel_hi:[1,0,0]
	v_fmac_f32_e32 v234, v203, v119
	v_fmac_f32_e32 v235, v136, v119
	v_fmac_f32_e32 v236, v137, v119
	v_fmac_f32_e32 v237, v138, v119
	v_pk_fma_f32 v[234:235], v[202:203], v[120:121], v[234:235] op_sel_hi:[1,0,1]
	v_pk_fma_f32 v[236:237], v[136:137], v[120:121], v[236:237] op_sel_hi:[1,0,1]
	v_pk_mul_f32 v[238:239], v[230:231], v[230:231]
	v_pk_mul_f32 v[240:241], v[232:233], v[232:233]
	v_pk_fma_f32 v[238:239], v[238:239], v[248:249], v[246:247]
	v_pk_fma_f32 v[240:241], v[240:241], v[248:249], v[246:247]
	v_pk_mul_f32 v[238:239], v[230:231], v[238:239]
	v_pk_mul_f32 v[240:241], v[232:233], v[240:241]
	v_exp_f32_e32 v238, v238
	v_exp_f32_e32 v239, v239
	v_exp_f32_e32 v240, v240
	v_exp_f32_e32 v241, v241
	v_pk_add_f32 v[238:239], v[238:239], 1.0 op_sel_hi:[1,0]
	v_pk_add_f32 v[240:241], v[240:241], 1.0 op_sel_hi:[1,0]
	v_rcp_f32_e32 v238, v238
	v_rcp_f32_e32 v239, v239
	v_rcp_f32_e32 v240, v240
	v_rcp_f32_e32 v241, v241
	v_pk_mul_f32 v[230:231], v[230:231], v[234:235]
	v_pk_mul_f32 v[232:233], v[232:233], v[236:237]
	v_pk_mul_f32 v[238:239], v[230:231], v[238:239]
	v_pk_mul_f32 v[240:241], v[232:233], v[240:241]
	v_cvt_pk_bf16_f32 v212, v238, v239
	v_cvt_pk_bf16_f32 v213, v240, v241
	s_mov_b64 vcc, s[30:31]
	s_nop 0
	v_mov_b32_dpp v214, v212 quad_perm:[1,0,3,2] row_mask:0xf bank_mask:0xf
	v_mov_b32_dpp v215, v213 quad_perm:[1,0,3,2] row_mask:0xf bank_mask:0xf
	v_perm_b32 v216, v214, v212, v253
	v_perm_b32 v217, v215, v213, v253
	s_nop 1
	v_mov_b32_dpp v218, v216 quad_perm:[2,3,0,1] row_mask:0xf bank_mask:0xf
	v_mov_b32_dpp v219, v217 quad_perm:[2,3,0,1] row_mask:0xf bank_mask:0xf
	v_cndmask_b32_e32 v176, v216, v219, vcc
	v_cndmask_b32_e32 v177, v218, v217, vcc
	s_waitcnt lgkmcnt(0)
	s_mov_b64 vcc, s[28:29]
	v_cndmask_b32_e32 v208, v110, v142, vcc
	v_cndmask_b32_e32 v209, v111, v143, vcc
	v_cndmask_b32_e32 v210, v98, v138, vcc
	v_cndmask_b32_e32 v211, v99, v139, vcc
	ds_bpermute_b32 v200, v252, v208
	ds_bpermute_b32 v201, v252, v209
	ds_bpermute_b32 v202, v252, v210
	ds_bpermute_b32 v203, v252, v211
	v_pk_fma_f32 v[230:231], v[44:45], v[124:125], v[128:129] op_sel_hi:[1,0,0]
	v_pk_fma_f32 v[232:233], v[46:47], v[124:125], v[128:129] op_sel_hi:[1,0,0]
	v_fmac_f32_e32 v230, v205, v125
	v_fmac_f32_e32 v231, v44, v125
	v_fmac_f32_e32 v232, v45, v125
	v_fmac_f32_e32 v233, v46, v125
	v_pk_fma_f32 v[230:231], v[204:205], v[126:127], v[230:231] op_sel_hi:[1,0,1]
	v_pk_fma_f32 v[232:233], v[44:45], v[126:127], v[232:233] op_sel_hi:[1,0,1]
	v_pk_fma_f32 v[234:235], v[40:41], v[130:131], v[134:135] op_sel_hi:[1,0,0]
	v_pk_fma_f32 v[236:237], v[42:43], v[130:131], v[134:135] op_sel_hi:[1,0,0]
	v_fmac_f32_e32 v234, v207, v131
	v_fmac_f32_e32 v235, v40, v131
	v_fmac_f32_e32 v236, v41, v131
	v_fmac_f32_e32 v237, v42, v131
	v_pk_fma_f32 v[234:235], v[206:207], v[132:133], v[234:235] op_sel_hi:[1,0,1]
	v_pk_fma_f32 v[236:237], v[40:41], v[132:133], v[236:237] op_sel_hi:[1,0,1]
	v_pk_mul_f32 v[238:239], v[230:231], v[230:231]
	v_pk_mul_f32 v[240:241], v[232:233], v[232:233]
	v_pk_fma_f32 v[238:239], v[238:239], v[248:249], v[246:247]
	v_pk_fma_f32 v[240:241], v[240:241], v[248:249], v[246:247]
	v_pk_mul_f32 v[238:239], v[230:231], v[238:239]
	v_pk_mul_f32 v[240:241], v[232:233], v[240:241]
	v_exp_f32_e32 v238, v238
	v_exp_f32_e32 v239, v239
	v_exp_f32_e32 v240, v240
	v_exp_f32_e32 v241, v241
	v_pk_add_f32 v[238:239], v[238:239], 1.0 op_sel_hi:[1,0]
	v_pk_add_f32 v[240:241], v[240:241], 1.0 op_sel_hi:[1,0]
	v_rcp_f32_e32 v238, v238
	v_rcp_f32_e32 v239, v239
	v_rcp_f32_e32 v240, v240
	v_rcp_f32_e32 v241, v241
	v_pk_mul_f32 v[230:231], v[230:231], v[234:235]
	v_pk_mul_f32 v[232:233], v[232:233], v[236:237]
	v_pk_mul_f32 v[238:239], v[230:231], v[238:239]
	v_pk_mul_f32 v[240:241], v[232:233], v[240:241]
	v_cvt_pk_bf16_f32 v212, v238, v239
	v_cvt_pk_bf16_f32 v213, v240, v241
	s_mov_b64 vcc, s[30:31]
	s_nop 0
	v_mov_b32_dpp v214, v212 quad_perm:[1,0,3,2] row_mask:0xf bank_mask:0xf
	v_mov_b32_dpp v215, v213 quad_perm:[1,0,3,2] row_mask:0xf bank_mask:0xf
	v_perm_b32 v216, v214, v212, v253
	v_perm_b32 v217, v215, v213, v253
	s_nop 1
	v_mov_b32_dpp v218, v216 quad_perm:[2,3,0,1] row_mask:0xf bank_mask:0xf
	v_mov_b32_dpp v219, v217 quad_perm:[2,3,0,1] row_mask:0xf bank_mask:0xf
	v_cndmask_b32_e32 v178, v216, v219, vcc
	v_cndmask_b32_e32 v179, v218, v217, vcc
	s_movk_i32 s15, 0xfe2
	v_cmp_gt_i32_e64 s[24:25], s15, v251
	s_add_u32 s84, s58, 0x29400
	s_addc_u32 s85, s59, 0
	s_mov_b64 exec, s[24:25]
	global_store_dwordx4 v250, v[176:179], s[84:85] nt
	s_mov_b64 exec, -1
	s_nop 0
	s_waitcnt lgkmcnt(0)
	s_mov_b64 vcc, s[28:29]
	v_cndmask_b32_e32 v208, v38, v46, vcc
	v_cndmask_b32_e32 v209, v39, v47, vcc
	v_cndmask_b32_e32 v210, v34, v42, vcc
	v_cndmask_b32_e32 v211, v35, v43, vcc
	ds_bpermute_b32 v204, v252, v208
	ds_bpermute_b32 v205, v252, v209
	ds_bpermute_b32 v206, v252, v210
	ds_bpermute_b32 v207, v252, v211
	v_pk_fma_f32 v[230:231], v[108:109], v[112:113], v[116:117] op_sel_hi:[1,0,0]
	v_pk_fma_f32 v[232:233], v[110:111], v[112:113], v[116:117] op_sel_hi:[1,0,0]
	v_fmac_f32_e32 v230, v201, v113
	v_fmac_f32_e32 v231, v108, v113
	v_fmac_f32_e32 v232, v109, v113
	v_fmac_f32_e32 v233, v110, v113
	v_pk_fma_f32 v[230:231], v[200:201], v[114:115], v[230:231] op_sel_hi:[1,0,1]
	v_pk_fma_f32 v[232:233], v[108:109], v[114:115], v[232:233] op_sel_hi:[1,0,1]
	v_pk_fma_f32 v[234:235], v[96:97], v[118:119], v[122:123] op_sel_hi:[1,0,0]
	v_pk_fma_f32 v[236:237], v[98:99], v[118:119], v[122:123] op_sel_hi:[1,0,0]
	v_fmac_f32_e32 v234, v203, v119
	v_fmac_f32_e32 v235, v96, v119
	v_fmac_f32_e32 v236, v97, v119
	v_fmac_f32_e32 v237, v98, v119
	v_pk_fma_f32 v[234:235], v[202:203], v[120:121], v[234:235] op_sel_hi:[1,0,1]
	v_pk_fma_f32 v[236:237], v[96:97], v[120:121], v[236:237] op_sel_hi:[1,0,1]
	v_pk_mul_f32 v[238:239], v[230:231], v[230:231]
	v_pk_mul_f32 v[240:241], v[232:233], v[232:233]
	v_pk_fma_f32 v[238:239], v[238:239], v[248:249], v[246:247]
	v_pk_fma_f32 v[240:241], v[240:241], v[248:249], v[246:247]
	v_pk_mul_f32 v[238:239], v[230:231], v[238:239]
	v_pk_mul_f32 v[240:241], v[232:233], v[240:241]
	v_exp_f32_e32 v238, v238
	v_exp_f32_e32 v239, v239
	v_exp_f32_e32 v240, v240
	v_exp_f32_e32 v241, v241
	v_pk_add_f32 v[238:239], v[238:239], 1.0 op_sel_hi:[1,0]
	v_pk_add_f32 v[240:241], v[240:241], 1.0 op_sel_hi:[1,0]
	v_rcp_f32_e32 v238, v238
	v_rcp_f32_e32 v239, v239
	v_rcp_f32_e32 v240, v240
	v_rcp_f32_e32 v241, v241
	v_pk_mul_f32 v[230:231], v[230:231], v[234:235]
	v_pk_mul_f32 v[232:233], v[232:233], v[236:237]
	v_pk_mul_f32 v[238:239], v[230:231], v[238:239]
	v_pk_mul_f32 v[240:241], v[232:233], v[240:241]
	v_cvt_pk_bf16_f32 v212, v238, v239
	v_cvt_pk_bf16_f32 v213, v240, v241
	s_mov_b64 vcc, s[30:31]
	s_nop 0
	v_mov_b32_dpp v214, v212 quad_perm:[1,0,3,2] row_mask:0xf bank_mask:0xf
	v_mov_b32_dpp v215, v213 quad_perm:[1,0,3,2] row_mask:0xf bank_mask:0xf
	v_perm_b32 v216, v214, v212, v253
	v_perm_b32 v217, v215, v213, v253
	s_nop 1
	v_mov_b32_dpp v218, v216 quad_perm:[2,3,0,1] row_mask:0xf bank_mask:0xf
	v_mov_b32_dpp v219, v217 quad_perm:[2,3,0,1] row_mask:0xf bank_mask:0xf
	v_cndmask_b32_e32 v180, v216, v219, vcc
	v_cndmask_b32_e32 v181, v218, v217, vcc
	s_waitcnt lgkmcnt(0)
	ds_bpermute_b32 v200, v252, v94
	ds_bpermute_b32 v201, v252, v95
	ds_bpermute_b32 v202, v252, v90
	ds_bpermute_b32 v203, v252, v91
	v_pk_fma_f32 v[230:231], v[36:37], v[124:125], v[128:129] op_sel_hi:[1,0,0]
	v_pk_fma_f32 v[232:233], v[38:39], v[124:125], v[128:129] op_sel_hi:[1,0,0]
	v_fmac_f32_e32 v230, v205, v125
	v_fmac_f32_e32 v231, v36, v125
	v_fmac_f32_e32 v232, v37, v125
	v_fmac_f32_e32 v233, v38, v125
	v_pk_fma_f32 v[230:231], v[204:205], v[126:127], v[230:231] op_sel_hi:[1,0,1]
	v_pk_fma_f32 v[232:233], v[36:37], v[126:127], v[232:233] op_sel_hi:[1,0,1]
	v_pk_fma_f32 v[234:235], v[32:33], v[130:131], v[134:135] op_sel_hi:[1,0,0]
	v_pk_fma_f32 v[236:237], v[34:35], v[130:131], v[134:135] op_sel_hi:[1,0,0]
	v_fmac_f32_e32 v234, v207, v131
	v_fmac_f32_e32 v235, v32, v131
	v_fmac_f32_e32 v236, v33, v131
	v_fmac_f32_e32 v237, v34, v131
	v_pk_fma_f32 v[234:235], v[206:207], v[132:133], v[234:235] op_sel_hi:[1,0,1]
	v_pk_fma_f32 v[236:237], v[32:33], v[132:133], v[236:237] op_sel_hi:[1,0,1]
	v_pk_mul_f32 v[238:239], v[230:231], v[230:231]
	v_pk_mul_f32 v[240:241], v[232:233], v[232:233]
	v_pk_fma_f32 v[238:239], v[238:239], v[248:249], v[246:247]
	v_pk_fma_f32 v[240:241], v[240:241], v[248:249], v[246:247]
	v_pk_mul_f32 v[238:239], v[230:231], v[238:239]
	v_pk_mul_f32 v[240:241], v[232:233], v[240:241]
	v_exp_f32_e32 v238, v238
	v_exp_f32_e32 v239, v239
	v_exp_f32_e32 v240, v240
	v_exp_f32_e32 v241, v241
	v_pk_add_f32 v[238:239], v[238:239], 1.0 op_sel_hi:[1,0]
	v_pk_add_f32 v[240:241], v[240:241], 1.0 op_sel_hi:[1,0]
	v_rcp_f32_e32 v238, v238
	v_rcp_f32_e32 v239, v239
	v_rcp_f32_e32 v240, v240
	v_rcp_f32_e32 v241, v241
	v_pk_mul_f32 v[230:231], v[230:231], v[234:235]
	v_pk_mul_f32 v[232:233], v[232:233], v[236:237]
	v_pk_mul_f32 v[238:239], v[230:231], v[238:239]
	v_pk_mul_f32 v[240:241], v[232:233], v[240:241]
	v_cvt_pk_bf16_f32 v212, v238, v239
	v_cvt_pk_bf16_f32 v213, v240, v241
	s_mov_b64 vcc, s[30:31]
	s_nop 0
	v_mov_b32_dpp v214, v212 quad_perm:[1,0,3,2] row_mask:0xf bank_mask:0xf
	v_mov_b32_dpp v215, v213 quad_perm:[1,0,3,2] row_mask:0xf bank_mask:0xf
	v_perm_b32 v216, v214, v212, v253
	v_perm_b32 v217, v215, v213, v253
	s_nop 1
	v_mov_b32_dpp v218, v216 quad_perm:[2,3,0,1] row_mask:0xf bank_mask:0xf
	v_mov_b32_dpp v219, v217 quad_perm:[2,3,0,1] row_mask:0xf bank_mask:0xf
	v_cndmask_b32_e32 v182, v216, v219, vcc
	v_cndmask_b32_e32 v183, v218, v217, vcc
	s_movk_i32 s15, 0xfd2
	v_cmp_gt_i32_e64 s[24:25], s15, v251
	s_add_u32 s84, s58, 0x3f400
	s_addc_u32 s85, s59, 0
	s_mov_b64 exec, s[24:25]
	global_store_dwordx4 v250, v[180:183], s[84:85] nt
	s_mov_b64 exec, -1
	s_nop 0
	s_waitcnt lgkmcnt(0)
	ds_bpermute_b32 v204, v252, v30
	ds_bpermute_b32 v205, v252, v31
	ds_bpermute_b32 v206, v252, v26
	ds_bpermute_b32 v207, v252, v27
	v_pk_fma_f32 v[230:231], v[92:93], v[112:113], v[116:117] op_sel_hi:[1,0,0]
	v_pk_fma_f32 v[232:233], v[94:95], v[112:113], v[116:117] op_sel_hi:[1,0,0]
	v_fmac_f32_e32 v230, v201, v113
	v_fmac_f32_e32 v231, v92, v113
	v_fmac_f32_e32 v232, v93, v113
	v_fmac_f32_e32 v233, v94, v113
	v_pk_fma_f32 v[230:231], v[200:201], v[114:115], v[230:231] op_sel_hi:[1,0,1]
	v_pk_fma_f32 v[232:233], v[92:93], v[114:115], v[232:233] op_sel_hi:[1,0,1]
	v_pk_fma_f32 v[234:235], v[88:89], v[118:119], v[122:123] op_sel_hi:[1,0,0]
	v_pk_fma_f32 v[236:237], v[90:91], v[118:119], v[122:123] op_sel_hi:[1,0,0]
	v_fmac_f32_e32 v234, v203, v119
	v_fmac_f32_e32 v235, v88, v119
	v_fmac_f32_e32 v236, v89, v119
	v_fmac_f32_e32 v237, v90, v119
	v_pk_fma_f32 v[234:235], v[202:203], v[120:121], v[234:235] op_sel_hi:[1,0,1]
	v_pk_fma_f32 v[236:237], v[88:89], v[120:121], v[236:237] op_sel_hi:[1,0,1]
	v_pk_mul_f32 v[238:239], v[230:231], v[230:231]
	v_pk_mul_f32 v[240:241], v[232:233], v[232:233]
	v_pk_fma_f32 v[238:239], v[238:239], v[248:249], v[246:247]
	v_pk_fma_f32 v[240:241], v[240:241], v[248:249], v[246:247]
	v_pk_mul_f32 v[238:239], v[230:231], v[238:239]
	v_pk_mul_f32 v[240:241], v[232:233], v[240:241]
	v_exp_f32_e32 v238, v238
	v_exp_f32_e32 v239, v239
	v_exp_f32_e32 v240, v240
	v_exp_f32_e32 v241, v241
	v_pk_add_f32 v[238:239], v[238:239], 1.0 op_sel_hi:[1,0]
	v_pk_add_f32 v[240:241], v[240:241], 1.0 op_sel_hi:[1,0]
	v_rcp_f32_e32 v238, v238
	v_rcp_f32_e32 v239, v239
	v_rcp_f32_e32 v240, v240
	v_rcp_f32_e32 v241, v241
	v_pk_mul_f32 v[230:231], v[230:231], v[234:235]
	v_pk_mul_f32 v[232:233], v[232:233], v[236:237]
	v_pk_mul_f32 v[238:239], v[230:231], v[238:239]
	v_pk_mul_f32 v[240:241], v[232:233], v[240:241]
	v_cvt_pk_bf16_f32 v212, v238, v239
	v_cvt_pk_bf16_f32 v213, v240, v241
	s_mov_b64 vcc, s[30:31]
	s_nop 0
	v_mov_b32_dpp v214, v212 quad_perm:[1,0,3,2] row_mask:0xf bank_mask:0xf
	v_mov_b32_dpp v215, v213 quad_perm:[1,0,3,2] row_mask:0xf bank_mask:0xf
	v_perm_b32 v216, v214, v212, v253
	v_perm_b32 v217, v215, v213, v253
	s_nop 1
	v_mov_b32_dpp v218, v216 quad_perm:[2,3,0,1] row_mask:0xf bank_mask:0xf
	v_mov_b32_dpp v219, v217 quad_perm:[2,3,0,1] row_mask:0xf bank_mask:0xf
	v_cndmask_b32_e32 v176, v216, v219, vcc
	v_cndmask_b32_e32 v177, v218, v217, vcc
	s_waitcnt lgkmcnt(0)
	s_mov_b64 vcc, s[28:29]
	v_cndmask_b32_e32 v208, v86, v94, vcc
	v_cndmask_b32_e32 v209, v87, v95, vcc
	v_cndmask_b32_e32 v210, v82, v90, vcc
	v_cndmask_b32_e32 v211, v83, v91, vcc
	ds_bpermute_b32 v200, v252, v208
	ds_bpermute_b32 v201, v252, v209
	ds_bpermute_b32 v202, v252, v210
	ds_bpermute_b32 v203, v252, v211
	v_pk_fma_f32 v[230:231], v[28:29], v[124:125], v[128:129] op_sel_hi:[1,0,0]
	v_pk_fma_f32 v[232:233], v[30:31], v[124:125], v[128:129] op_sel_hi:[1,0,0]
	v_fmac_f32_e32 v230, v205, v125
	v_fmac_f32_e32 v231, v28, v125
	v_fmac_f32_e32 v232, v29, v125
	v_fmac_f32_e32 v233, v30, v125
	v_pk_fma_f32 v[230:231], v[204:205], v[126:127], v[230:231] op_sel_hi:[1,0,1]
	v_pk_fma_f32 v[232:233], v[28:29], v[126:127], v[232:233] op_sel_hi:[1,0,1]
	v_pk_fma_f32 v[234:235], v[24:25], v[130:131], v[134:135] op_sel_hi:[1,0,0]
	v_pk_fma_f32 v[236:237], v[26:27], v[130:131], v[134:135] op_sel_hi:[1,0,0]
	v_fmac_f32_e32 v234, v207, v131
	v_fmac_f32_e32 v235, v24, v131
	v_fmac_f32_e32 v236, v25, v131
	v_fmac_f32_e32 v237, v26, v131
	v_pk_fma_f32 v[234:235], v[206:207], v[132:133], v[234:235] op_sel_hi:[1,0,1]
	v_pk_fma_f32 v[236:237], v[24:25], v[132:133], v[236:237] op_sel_hi:[1,0,1]
	v_pk_mul_f32 v[238:239], v[230:231], v[230:231]
	v_pk_mul_f32 v[240:241], v[232:233], v[232:233]
	v_pk_fma_f32 v[238:239], v[238:239], v[248:249], v[246:247]
	v_pk_fma_f32 v[240:241], v[240:241], v[248:249], v[246:247]
	v_pk_mul_f32 v[238:239], v[230:231], v[238:239]
	v_pk_mul_f32 v[240:241], v[232:233], v[240:241]
	v_exp_f32_e32 v238, v238
	v_exp_f32_e32 v239, v239
	v_exp_f32_e32 v240, v240
	v_exp_f32_e32 v241, v241
	v_pk_add_f32 v[238:239], v[238:239], 1.0 op_sel_hi:[1,0]
	v_pk_add_f32 v[240:241], v[240:241], 1.0 op_sel_hi:[1,0]
	v_rcp_f32_e32 v238, v238
	v_rcp_f32_e32 v239, v239
	v_rcp_f32_e32 v240, v240
	v_rcp_f32_e32 v241, v241
	v_pk_mul_f32 v[230:231], v[230:231], v[234:235]
	v_pk_mul_f32 v[232:233], v[232:233], v[236:237]
	v_pk_mul_f32 v[238:239], v[230:231], v[238:239]
	v_pk_mul_f32 v[240:241], v[232:233], v[240:241]
	v_cvt_pk_bf16_f32 v212, v238, v239
	v_cvt_pk_bf16_f32 v213, v240, v241
	s_mov_b64 vcc, s[30:31]
	s_nop 0
	v_mov_b32_dpp v214, v212 quad_perm:[1,0,3,2] row_mask:0xf bank_mask:0xf
	v_mov_b32_dpp v215, v213 quad_perm:[1,0,3,2] row_mask:0xf bank_mask:0xf
	v_perm_b32 v216, v214, v212, v253
	v_perm_b32 v217, v215, v213, v253
	s_nop 1
	v_mov_b32_dpp v218, v216 quad_perm:[2,3,0,1] row_mask:0xf bank_mask:0xf
	v_mov_b32_dpp v219, v217 quad_perm:[2,3,0,1] row_mask:0xf bank_mask:0xf
	v_cndmask_b32_e32 v178, v216, v219, vcc
	v_cndmask_b32_e32 v179, v218, v217, vcc
	s_movk_i32 s15, 0xf86
	v_cmp_gt_i32_e64 s[24:25], s15, v251
	s_add_u32 s84, s58, 0xa7c00
	s_addc_u32 s85, s59, 0
	s_and_b64 s[24:25], s[24:25], s[36:37]
	s_mov_b64 exec, s[24:25]
	global_store_dwordx4 v250, v[176:179], s[84:85] nt
	s_mov_b64 exec, -1
	s_nop 0
	s_waitcnt lgkmcnt(0)
	s_mov_b64 vcc, s[28:29]
	v_cndmask_b32_e32 v208, v22, v30, vcc
	v_cndmask_b32_e32 v209, v23, v31, vcc
	v_cndmask_b32_e32 v210, v18, v26, vcc
	v_cndmask_b32_e32 v211, v19, v27, vcc
	ds_bpermute_b32 v204, v252, v208
	ds_bpermute_b32 v205, v252, v209
	ds_bpermute_b32 v206, v252, v210
	ds_bpermute_b32 v207, v252, v211
	v_pk_fma_f32 v[230:231], v[84:85], v[112:113], v[116:117] op_sel_hi:[1,0,0]
	v_pk_fma_f32 v[232:233], v[86:87], v[112:113], v[116:117] op_sel_hi:[1,0,0]
	v_fmac_f32_e32 v230, v201, v113
	v_fmac_f32_e32 v231, v84, v113
	v_fmac_f32_e32 v232, v85, v113
	v_fmac_f32_e32 v233, v86, v113
	v_pk_fma_f32 v[230:231], v[200:201], v[114:115], v[230:231] op_sel_hi:[1,0,1]
	v_pk_fma_f32 v[232:233], v[84:85], v[114:115], v[232:233] op_sel_hi:[1,0,1]
	v_pk_fma_f32 v[234:235], v[80:81], v[118:119], v[122:123] op_sel_hi:[1,0,0]
	v_pk_fma_f32 v[236:237], v[82:83], v[118:119], v[122:123] op_sel_hi:[1,0,0]
	v_fmac_f32_e32 v234, v203, v119
	v_fmac_f32_e32 v235, v80, v119
	v_fmac_f32_e32 v236, v81, v119
	v_fmac_f32_e32 v237, v82, v119
	v_pk_fma_f32 v[234:235], v[202:203], v[120:121], v[234:235] op_sel_hi:[1,0,1]
	v_pk_fma_f32 v[236:237], v[80:81], v[120:121], v[236:237] op_sel_hi:[1,0,1]
	v_pk_mul_f32 v[238:239], v[230:231], v[230:231]
	v_pk_mul_f32 v[240:241], v[232:233], v[232:233]
	v_pk_fma_f32 v[238:239], v[238:239], v[248:249], v[246:247]
	v_pk_fma_f32 v[240:241], v[240:241], v[248:249], v[246:247]
	v_pk_mul_f32 v[238:239], v[230:231], v[238:239]
	v_pk_mul_f32 v[240:241], v[232:233], v[240:241]
	v_exp_f32_e32 v238, v238
	v_exp_f32_e32 v239, v239
	v_exp_f32_e32 v240, v240
	v_exp_f32_e32 v241, v241
	v_pk_add_f32 v[238:239], v[238:239], 1.0 op_sel_hi:[1,0]
	v_pk_add_f32 v[240:241], v[240:241], 1.0 op_sel_hi:[1,0]
	v_rcp_f32_e32 v238, v238
	v_rcp_f32_e32 v239, v239
	v_rcp_f32_e32 v240, v240
	v_rcp_f32_e32 v241, v241
	v_pk_mul_f32 v[230:231], v[230:231], v[234:235]
	v_pk_mul_f32 v[232:233], v[232:233], v[236:237]
	v_pk_mul_f32 v[238:239], v[230:231], v[238:239]
	v_pk_mul_f32 v[240:241], v[232:233], v[240:241]
	v_cvt_pk_bf16_f32 v212, v238, v239
	v_cvt_pk_bf16_f32 v213, v240, v241
	s_mov_b64 vcc, s[30:31]
	s_nop 0
	v_mov_b32_dpp v214, v212 quad_perm:[1,0,3,2] row_mask:0xf bank_mask:0xf
	v_mov_b32_dpp v215, v213 quad_perm:[1,0,3,2] row_mask:0xf bank_mask:0xf
	v_perm_b32 v216, v214, v212, v253
	v_perm_b32 v217, v215, v213, v253
	s_nop 1
	v_mov_b32_dpp v218, v216 quad_perm:[2,3,0,1] row_mask:0xf bank_mask:0xf
	v_mov_b32_dpp v219, v217 quad_perm:[2,3,0,1] row_mask:0xf bank_mask:0xf
	v_cndmask_b32_e32 v180, v216, v219, vcc
	v_cndmask_b32_e32 v181, v218, v217, vcc
	s_waitcnt lgkmcnt(0)
	s_mov_b64 vcc, s[28:29]
	v_cndmask_b32_e32 v208, v78, v86, vcc
	v_cndmask_b32_e32 v209, v79, v87, vcc
	v_cndmask_b32_e32 v210, v74, v82, vcc
	v_cndmask_b32_e32 v211, v75, v83, vcc
	ds_bpermute_b32 v200, v252, v208
	ds_bpermute_b32 v201, v252, v209
	ds_bpermute_b32 v202, v252, v210
	ds_bpermute_b32 v203, v252, v211
	v_pk_fma_f32 v[230:231], v[20:21], v[124:125], v[128:129] op_sel_hi:[1,0,0]
	v_pk_fma_f32 v[232:233], v[22:23], v[124:125], v[128:129] op_sel_hi:[1,0,0]
	v_fmac_f32_e32 v230, v205, v125
	v_fmac_f32_e32 v231, v20, v125
	v_fmac_f32_e32 v232, v21, v125
	v_fmac_f32_e32 v233, v22, v125
	v_pk_fma_f32 v[230:231], v[204:205], v[126:127], v[230:231] op_sel_hi:[1,0,1]
	v_pk_fma_f32 v[232:233], v[20:21], v[126:127], v[232:233] op_sel_hi:[1,0,1]
	v_pk_fma_f32 v[234:235], v[16:17], v[130:131], v[134:135] op_sel_hi:[1,0,0]
	v_pk_fma_f32 v[236:237], v[18:19], v[130:131], v[134:135] op_sel_hi:[1,0,0]
	v_fmac_f32_e32 v234, v207, v131
	v_fmac_f32_e32 v235, v16, v131
	v_fmac_f32_e32 v236, v17, v131
	v_fmac_f32_e32 v237, v18, v131
	v_pk_fma_f32 v[234:235], v[206:207], v[132:133], v[234:235] op_sel_hi:[1,0,1]
	v_pk_fma_f32 v[236:237], v[16:17], v[132:133], v[236:237] op_sel_hi:[1,0,1]
	v_pk_mul_f32 v[238:239], v[230:231], v[230:231]
	v_pk_mul_f32 v[240:241], v[232:233], v[232:233]
	v_pk_fma_f32 v[238:239], v[238:239], v[248:249], v[246:247]
	v_pk_fma_f32 v[240:241], v[240:241], v[248:249], v[246:247]
	v_pk_mul_f32 v[238:239], v[230:231], v[238:239]
	v_pk_mul_f32 v[240:241], v[232:233], v[240:241]
	v_exp_f32_e32 v238, v238
	v_exp_f32_e32 v239, v239
	v_exp_f32_e32 v240, v240
	v_exp_f32_e32 v241, v241
	v_pk_add_f32 v[238:239], v[238:239], 1.0 op_sel_hi:[1,0]
	v_pk_add_f32 v[240:241], v[240:241], 1.0 op_sel_hi:[1,0]
	v_rcp_f32_e32 v238, v238
	v_rcp_f32_e32 v239, v239
	v_rcp_f32_e32 v240, v240
	v_rcp_f32_e32 v241, v241
	v_pk_mul_f32 v[230:231], v[230:231], v[234:235]
	v_pk_mul_f32 v[232:233], v[232:233], v[236:237]
	v_pk_mul_f32 v[238:239], v[230:231], v[238:239]
	v_pk_mul_f32 v[240:241], v[232:233], v[240:241]
	v_cvt_pk_bf16_f32 v212, v238, v239
	v_cvt_pk_bf16_f32 v213, v240, v241
	s_mov_b64 vcc, s[30:31]
	s_nop 0
	v_mov_b32_dpp v214, v212 quad_perm:[1,0,3,2] row_mask:0xf bank_mask:0xf
	v_mov_b32_dpp v215, v213 quad_perm:[1,0,3,2] row_mask:0xf bank_mask:0xf
	v_perm_b32 v216, v214, v212, v253
	v_perm_b32 v217, v215, v213, v253
	s_nop 1
	v_mov_b32_dpp v218, v216 quad_perm:[2,3,0,1] row_mask:0xf bank_mask:0xf
	v_mov_b32_dpp v219, v217 quad_perm:[2,3,0,1] row_mask:0xf bank_mask:0xf
	v_cndmask_b32_e32 v182, v216, v219, vcc
	v_cndmask_b32_e32 v183, v218, v217, vcc
	s_movk_i32 s15, 0xf76
	v_cmp_gt_i32_e64 s[24:25], s15, v251
	s_add_u32 s84, s58, 0xbdc00
	s_addc_u32 s85, s59, 0
	s_mov_b64 exec, s[24:25]
	global_store_dwordx4 v250, v[180:183], s[84:85] nt
	s_mov_b64 exec, -1
	s_nop 0
	s_waitcnt lgkmcnt(0)
	s_mov_b64 vcc, s[28:29]
	v_cndmask_b32_e32 v208, v14, v22, vcc
	v_cndmask_b32_e32 v209, v15, v23, vcc
	v_cndmask_b32_e32 v210, v10, v18, vcc
	v_cndmask_b32_e32 v211, v11, v19, vcc
	ds_bpermute_b32 v204, v252, v208
	ds_bpermute_b32 v205, v252, v209
	ds_bpermute_b32 v206, v252, v210
	ds_bpermute_b32 v207, v252, v211
	v_pk_fma_f32 v[230:231], v[76:77], v[112:113], v[116:117] op_sel_hi:[1,0,0]
	v_pk_fma_f32 v[232:233], v[78:79], v[112:113], v[116:117] op_sel_hi:[1,0,0]
	v_fmac_f32_e32 v230, v201, v113
	v_fmac_f32_e32 v231, v76, v113
	v_fmac_f32_e32 v232, v77, v113
	v_fmac_f32_e32 v233, v78, v113
	v_pk_fma_f32 v[230:231], v[200:201], v[114:115], v[230:231] op_sel_hi:[1,0,1]
	v_pk_fma_f32 v[232:233], v[76:77], v[114:115], v[232:233] op_sel_hi:[1,0,1]
	v_pk_fma_f32 v[234:235], v[72:73], v[118:119], v[122:123] op_sel_hi:[1,0,0]
	v_pk_fma_f32 v[236:237], v[74:75], v[118:119], v[122:123] op_sel_hi:[1,0,0]
	v_fmac_f32_e32 v234, v203, v119
	v_fmac_f32_e32 v235, v72, v119
	v_fmac_f32_e32 v236, v73, v119
	v_fmac_f32_e32 v237, v74, v119
	v_pk_fma_f32 v[234:235], v[202:203], v[120:121], v[234:235] op_sel_hi:[1,0,1]
	v_pk_fma_f32 v[236:237], v[72:73], v[120:121], v[236:237] op_sel_hi:[1,0,1]
	v_pk_mul_f32 v[238:239], v[230:231], v[230:231]
	v_pk_mul_f32 v[240:241], v[232:233], v[232:233]
	v_pk_fma_f32 v[238:239], v[238:239], v[248:249], v[246:247]
	v_pk_fma_f32 v[240:241], v[240:241], v[248:249], v[246:247]
	v_pk_mul_f32 v[238:239], v[230:231], v[238:239]
	v_pk_mul_f32 v[240:241], v[232:233], v[240:241]
	v_exp_f32_e32 v238, v238
	v_exp_f32_e32 v239, v239
	v_exp_f32_e32 v240, v240
	v_exp_f32_e32 v241, v241
	v_pk_add_f32 v[238:239], v[238:239], 1.0 op_sel_hi:[1,0]
	v_pk_add_f32 v[240:241], v[240:241], 1.0 op_sel_hi:[1,0]
	v_rcp_f32_e32 v238, v238
	v_rcp_f32_e32 v239, v239
	v_rcp_f32_e32 v240, v240
	v_rcp_f32_e32 v241, v241
	v_pk_mul_f32 v[230:231], v[230:231], v[234:235]
	v_pk_mul_f32 v[232:233], v[232:233], v[236:237]
	v_pk_mul_f32 v[238:239], v[230:231], v[238:239]
	v_pk_mul_f32 v[240:241], v[232:233], v[240:241]
	v_cvt_pk_bf16_f32 v212, v238, v239
	v_cvt_pk_bf16_f32 v213, v240, v241
	s_mov_b64 vcc, s[30:31]
	s_nop 0
	v_mov_b32_dpp v214, v212 quad_perm:[1,0,3,2] row_mask:0xf bank_mask:0xf
	v_mov_b32_dpp v215, v213 quad_perm:[1,0,3,2] row_mask:0xf bank_mask:0xf
	v_perm_b32 v216, v214, v212, v253
	v_perm_b32 v217, v215, v213, v253
	s_nop 1
	v_mov_b32_dpp v218, v216 quad_perm:[2,3,0,1] row_mask:0xf bank_mask:0xf
	v_mov_b32_dpp v219, v217 quad_perm:[2,3,0,1] row_mask:0xf bank_mask:0xf
	v_cndmask_b32_e32 v176, v216, v219, vcc
	v_cndmask_b32_e32 v177, v218, v217, vcc
	s_waitcnt lgkmcnt(0)
	s_mov_b64 vcc, s[28:29]
	v_cndmask_b32_e32 v208, v70, v78, vcc
	v_cndmask_b32_e32 v209, v71, v79, vcc
	v_cndmask_b32_e32 v210, v66, v74, vcc
	v_cndmask_b32_e32 v211, v67, v75, vcc
	ds_bpermute_b32 v200, v252, v208
	ds_bpermute_b32 v201, v252, v209
	ds_bpermute_b32 v202, v252, v210
	ds_bpermute_b32 v203, v252, v211
	v_pk_fma_f32 v[230:231], v[12:13], v[124:125], v[128:129] op_sel_hi:[1,0,0]
	v_pk_fma_f32 v[232:233], v[14:15], v[124:125], v[128:129] op_sel_hi:[1,0,0]
	v_fmac_f32_e32 v230, v205, v125
	v_fmac_f32_e32 v231, v12, v125
	v_fmac_f32_e32 v232, v13, v125
	v_fmac_f32_e32 v233, v14, v125
	v_pk_fma_f32 v[230:231], v[204:205], v[126:127], v[230:231] op_sel_hi:[1,0,1]
	v_pk_fma_f32 v[232:233], v[12:13], v[126:127], v[232:233] op_sel_hi:[1,0,1]
	v_pk_fma_f32 v[234:235], v[8:9], v[130:131], v[134:135] op_sel_hi:[1,0,0]
	v_pk_fma_f32 v[236:237], v[10:11], v[130:131], v[134:135] op_sel_hi:[1,0,0]
	v_fmac_f32_e32 v234, v207, v131
	v_fmac_f32_e32 v235, v8, v131
	v_fmac_f32_e32 v236, v9, v131
	v_fmac_f32_e32 v237, v10, v131
	v_pk_fma_f32 v[234:235], v[206:207], v[132:133], v[234:235] op_sel_hi:[1,0,1]
	v_pk_fma_f32 v[236:237], v[8:9], v[132:133], v[236:237] op_sel_hi:[1,0,1]
	v_pk_mul_f32 v[238:239], v[230:231], v[230:231]
	v_pk_mul_f32 v[240:241], v[232:233], v[232:233]
	v_pk_fma_f32 v[238:239], v[238:239], v[248:249], v[246:247]
	v_pk_fma_f32 v[240:241], v[240:241], v[248:249], v[246:247]
	v_pk_mul_f32 v[238:239], v[230:231], v[238:239]
	v_pk_mul_f32 v[240:241], v[232:233], v[240:241]
	v_exp_f32_e32 v238, v238
	v_exp_f32_e32 v239, v239
	v_exp_f32_e32 v240, v240
	v_exp_f32_e32 v241, v241
	v_pk_add_f32 v[238:239], v[238:239], 1.0 op_sel_hi:[1,0]
	v_pk_add_f32 v[240:241], v[240:241], 1.0 op_sel_hi:[1,0]
	v_rcp_f32_e32 v238, v238
	v_rcp_f32_e32 v239, v239
	v_rcp_f32_e32 v240, v240
	v_rcp_f32_e32 v241, v241
	v_pk_mul_f32 v[230:231], v[230:231], v[234:235]
	v_pk_mul_f32 v[232:233], v[232:233], v[236:237]
	v_pk_mul_f32 v[238:239], v[230:231], v[238:239]
	v_pk_mul_f32 v[240:241], v[232:233], v[240:241]
	v_cvt_pk_bf16_f32 v212, v238, v239
	v_cvt_pk_bf16_f32 v213, v240, v241
	s_mov_b64 vcc, s[30:31]
	s_nop 0
	v_mov_b32_dpp v214, v212 quad_perm:[1,0,3,2] row_mask:0xf bank_mask:0xf
	v_mov_b32_dpp v215, v213 quad_perm:[1,0,3,2] row_mask:0xf bank_mask:0xf
	v_perm_b32 v216, v214, v212, v253
	v_perm_b32 v217, v215, v213, v253
	s_nop 1
	v_mov_b32_dpp v218, v216 quad_perm:[2,3,0,1] row_mask:0xf bank_mask:0xf
	v_mov_b32_dpp v219, v217 quad_perm:[2,3,0,1] row_mask:0xf bank_mask:0xf
	v_cndmask_b32_e32 v178, v216, v219, vcc
	v_cndmask_b32_e32 v179, v218, v217, vcc
	s_movk_i32 s15, 0xf66
	v_cmp_gt_i32_e64 s[24:25], s15, v251
	s_add_u32 s84, s58, 0xd3c00
	s_addc_u32 s85, s59, 0
	s_mov_b64 exec, s[24:25]
	global_store_dwordx4 v250, v[176:179], s[84:85] nt
	s_mov_b64 exec, -1
	s_nop 0
	s_waitcnt lgkmcnt(0)
	s_mov_b64 vcc, s[28:29]
	v_cndmask_b32_e32 v208, v6, v14, vcc
	v_cndmask_b32_e32 v209, v7, v15, vcc
	v_cndmask_b32_e32 v210, v2, v10, vcc
	v_cndmask_b32_e32 v211, v3, v11, vcc
	ds_bpermute_b32 v204, v252, v208
	ds_bpermute_b32 v205, v252, v209
	ds_bpermute_b32 v206, v252, v210
	ds_bpermute_b32 v207, v252, v211
	v_pk_fma_f32 v[230:231], v[68:69], v[112:113], v[116:117] op_sel_hi:[1,0,0]
	v_pk_fma_f32 v[232:233], v[70:71], v[112:113], v[116:117] op_sel_hi:[1,0,0]
	v_fmac_f32_e32 v230, v201, v113
	v_fmac_f32_e32 v231, v68, v113
	v_fmac_f32_e32 v232, v69, v113
	v_fmac_f32_e32 v233, v70, v113
	v_pk_fma_f32 v[230:231], v[200:201], v[114:115], v[230:231] op_sel_hi:[1,0,1]
	v_pk_fma_f32 v[232:233], v[68:69], v[114:115], v[232:233] op_sel_hi:[1,0,1]
	v_pk_fma_f32 v[234:235], v[64:65], v[118:119], v[122:123] op_sel_hi:[1,0,0]
	v_pk_fma_f32 v[236:237], v[66:67], v[118:119], v[122:123] op_sel_hi:[1,0,0]
	v_fmac_f32_e32 v234, v203, v119
	v_fmac_f32_e32 v235, v64, v119
	v_fmac_f32_e32 v236, v65, v119
	v_fmac_f32_e32 v237, v66, v119
	v_pk_fma_f32 v[234:235], v[202:203], v[120:121], v[234:235] op_sel_hi:[1,0,1]
	v_pk_fma_f32 v[236:237], v[64:65], v[120:121], v[236:237] op_sel_hi:[1,0,1]
	v_pk_mul_f32 v[238:239], v[230:231], v[230:231]
	v_pk_mul_f32 v[240:241], v[232:233], v[232:233]
	v_pk_fma_f32 v[238:239], v[238:239], v[248:249], v[246:247]
	v_pk_fma_f32 v[240:241], v[240:241], v[248:249], v[246:247]
	v_pk_mul_f32 v[238:239], v[230:231], v[238:239]
	v_pk_mul_f32 v[240:241], v[232:233], v[240:241]
	v_exp_f32_e32 v238, v238
	v_exp_f32_e32 v239, v239
	v_exp_f32_e32 v240, v240
	v_exp_f32_e32 v241, v241
	v_pk_add_f32 v[238:239], v[238:239], 1.0 op_sel_hi:[1,0]
	v_pk_add_f32 v[240:241], v[240:241], 1.0 op_sel_hi:[1,0]
	v_rcp_f32_e32 v238, v238
	v_rcp_f32_e32 v239, v239
	v_rcp_f32_e32 v240, v240
	v_rcp_f32_e32 v241, v241
	v_pk_mul_f32 v[230:231], v[230:231], v[234:235]
	v_pk_mul_f32 v[232:233], v[232:233], v[236:237]
	v_pk_mul_f32 v[238:239], v[230:231], v[238:239]
	v_pk_mul_f32 v[240:241], v[232:233], v[240:241]
	v_cvt_pk_bf16_f32 v212, v238, v239
	v_cvt_pk_bf16_f32 v213, v240, v241
	s_mov_b64 vcc, s[30:31]
	s_nop 0
	v_mov_b32_dpp v214, v212 quad_perm:[1,0,3,2] row_mask:0xf bank_mask:0xf
	v_mov_b32_dpp v215, v213 quad_perm:[1,0,3,2] row_mask:0xf bank_mask:0xf
	v_perm_b32 v216, v214, v212, v253
	v_perm_b32 v217, v215, v213, v253
	s_nop 1
	v_mov_b32_dpp v218, v216 quad_perm:[2,3,0,1] row_mask:0xf bank_mask:0xf
	v_mov_b32_dpp v219, v217 quad_perm:[2,3,0,1] row_mask:0xf bank_mask:0xf
	v_cndmask_b32_e32 v180, v216, v219, vcc
	v_cndmask_b32_e32 v181, v218, v217, vcc
	s_waitcnt lgkmcnt(0)
	v_pk_fma_f32 v[230:231], v[4:5], v[124:125], v[128:129] op_sel_hi:[1,0,0]
	v_pk_fma_f32 v[232:233], v[6:7], v[124:125], v[128:129] op_sel_hi:[1,0,0]
	v_fmac_f32_e32 v230, v205, v125
	v_fmac_f32_e32 v231, v4, v125
	v_fmac_f32_e32 v232, v5, v125
	v_fmac_f32_e32 v233, v6, v125
	v_pk_fma_f32 v[230:231], v[204:205], v[126:127], v[230:231] op_sel_hi:[1,0,1]
	v_pk_fma_f32 v[232:233], v[4:5], v[126:127], v[232:233] op_sel_hi:[1,0,1]
	v_pk_fma_f32 v[234:235], v[0:1], v[130:131], v[134:135] op_sel_hi:[1,0,0]
	v_pk_fma_f32 v[236:237], v[2:3], v[130:131], v[134:135] op_sel_hi:[1,0,0]
	v_fmac_f32_e32 v234, v207, v131
	v_fmac_f32_e32 v235, v0, v131
	v_fmac_f32_e32 v236, v1, v131
	v_fmac_f32_e32 v237, v2, v131
	v_pk_fma_f32 v[234:235], v[206:207], v[132:133], v[234:235] op_sel_hi:[1,0,1]
	v_pk_fma_f32 v[236:237], v[0:1], v[132:133], v[236:237] op_sel_hi:[1,0,1]
	v_pk_mul_f32 v[238:239], v[230:231], v[230:231]
	v_pk_mul_f32 v[240:241], v[232:233], v[232:233]
	v_pk_fma_f32 v[238:239], v[238:239], v[248:249], v[246:247]
	v_pk_fma_f32 v[240:241], v[240:241], v[248:249], v[246:247]
	v_pk_mul_f32 v[238:239], v[230:231], v[238:239]
	v_pk_mul_f32 v[240:241], v[232:233], v[240:241]
	v_exp_f32_e32 v238, v238
	v_exp_f32_e32 v239, v239
	v_exp_f32_e32 v240, v240
	v_exp_f32_e32 v241, v241
	v_pk_add_f32 v[238:239], v[238:239], 1.0 op_sel_hi:[1,0]
	v_pk_add_f32 v[240:241], v[240:241], 1.0 op_sel_hi:[1,0]
	v_rcp_f32_e32 v238, v238
	v_rcp_f32_e32 v239, v239
	v_rcp_f32_e32 v240, v240
	v_rcp_f32_e32 v241, v241
	v_pk_mul_f32 v[230:231], v[230:231], v[234:235]
	v_pk_mul_f32 v[232:233], v[232:233], v[236:237]
	v_pk_mul_f32 v[238:239], v[230:231], v[238:239]
	v_pk_mul_f32 v[240:241], v[232:233], v[240:241]
	v_cvt_pk_bf16_f32 v212, v238, v239
	v_cvt_pk_bf16_f32 v213, v240, v241
	s_mov_b64 vcc, s[30:31]
	s_nop 0
	v_mov_b32_dpp v214, v212 quad_perm:[1,0,3,2] row_mask:0xf bank_mask:0xf
	v_mov_b32_dpp v215, v213 quad_perm:[1,0,3,2] row_mask:0xf bank_mask:0xf
	v_perm_b32 v216, v214, v212, v253
	v_perm_b32 v217, v215, v213, v253
	s_nop 1
	v_mov_b32_dpp v218, v216 quad_perm:[2,3,0,1] row_mask:0xf bank_mask:0xf
	v_mov_b32_dpp v219, v217 quad_perm:[2,3,0,1] row_mask:0xf bank_mask:0xf
	v_cndmask_b32_e32 v182, v216, v219, vcc
	v_cndmask_b32_e32 v183, v218, v217, vcc
	s_movk_i32 s15, 0xf56
	v_cmp_gt_i32_e64 s[24:25], s15, v251
	s_add_u32 s84, s58, 0xe9c00
	s_addc_u32 s85, s59, 0
	s_mov_b64 exec, s[24:25]
	global_store_dwordx4 v250, v[180:183], s[84:85] nt
	s_mov_b64 exec, -1
	s_nop 0
	s_mov_b64 s[0:1], -1
	s_branch .LBB0_619
	s_nop 0
	s_nop 0
	s_nop 0
	s_nop 0
	s_nop 0
	s_nop 0
	s_nop 0
	s_nop 0
	s_nop 0
	s_nop 0
	s_nop 0
	s_nop 0
	s_nop 0
	s_nop 0
	s_nop 0
	s_nop 0
	s_nop 0
	s_nop 0
	s_nop 0
	s_nop 0
	s_nop 0
	s_nop 0
	s_nop 0
	s_nop 0
	s_nop 0
	s_nop 0
	s_nop 0
	s_nop 0
	s_nop 0
	s_nop 0
	s_nop 0
	s_nop 0
	s_nop 0
	s_nop 0
	s_nop 0
	s_nop 0
	s_nop 0
	s_nop 0
	s_nop 0
	s_nop 0
	s_nop 0
	s_nop 0
	s_nop 0
	s_nop 0
	s_nop 0
	s_nop 0
	s_nop 0
	s_nop 0
	s_nop 0
	s_nop 0
	s_nop 0
	s_nop 0
	s_nop 0
	s_nop 0
	s_nop 0
	s_nop 0
	s_nop 0
	s_nop 0
	s_nop 0
	s_nop 0
	s_nop 0
	s_nop 0
	s_nop 0
	s_nop 0
	s_nop 0
	s_nop 0
	s_nop 0
	s_nop 0
	s_nop 0
	s_nop 0
	s_nop 0
	s_nop 0
	s_nop 0
	s_nop 0
	s_nop 0
	s_nop 0
	s_nop 0
	s_nop 0
	s_nop 0
	s_nop 0
	s_nop 0
	s_nop 0
	s_nop 0
	s_nop 0
	s_nop 0
	s_nop 0
	s_nop 0
	s_nop 0
	s_nop 0
	s_nop 0
	s_nop 0
	s_nop 0
	s_nop 0
	s_nop 0
	s_nop 0
	s_nop 0
	s_nop 0
	s_nop 0
	s_nop 0
	s_nop 0
	s_nop 0
	s_nop 0
	s_nop 0
	s_nop 0
	s_nop 0
	s_nop 0
	s_nop 0
	s_nop 0
	s_nop 0
	s_nop 0
	s_nop 0
	s_nop 0
	s_nop 0
	s_nop 0
	s_nop 0
	s_nop 0
	s_nop 0
	s_nop 0
	s_nop 0
	s_nop 0
	s_nop 0
	s_nop 0
	s_nop 0
	s_nop 0
	s_nop 0
	s_nop 0
	s_nop 0
	s_nop 0
	s_nop 0
	s_nop 0
	s_nop 0
	s_nop 0
	s_nop 0
	s_nop 0
	s_nop 0
	s_nop 0
	s_nop 0
	s_nop 0
	s_nop 0
	s_nop 0
	s_nop 0
	s_nop 0
	s_nop 0
	s_nop 0
	s_nop 0
	s_nop 0
	s_nop 0
	s_nop 0
	s_nop 0
	s_nop 0
	s_nop 0
	s_nop 0
	s_nop 0
	s_nop 0
	s_nop 0
	s_nop 0
	s_nop 0
	s_nop 0
	s_nop 0
	s_nop 0
	s_nop 0
	s_nop 0
	s_nop 0
	s_nop 0
	s_nop 0
	s_nop 0
	s_nop 0
	s_nop 0
	s_nop 0
	s_nop 0
	s_nop 0
	s_nop 0
	s_nop 0
	s_nop 0
	s_nop 0
	s_nop 0
	s_nop 0
	s_nop 0
	s_nop 0
	s_nop 0
	s_nop 0
	s_nop 0
	s_nop 0
	s_nop 0
	s_nop 0
	s_nop 0
	s_nop 0
	s_nop 0
	s_nop 0
	s_nop 0
	s_nop 0
	s_nop 0
	s_nop 0
	s_nop 0
	s_nop 0
	s_nop 0
	s_nop 0
	s_nop 0
	s_nop 0
	s_nop 0
	s_nop 0
	s_nop 0
	s_nop 0
	s_nop 0
	s_nop 0
	s_nop 0
	s_nop 0
	s_nop 0
	s_nop 0
	s_nop 0
